# ssm pass-1 unit set-up: the four coefficient row loads issued together at the top of the unit
# baseline (speedup 1.0000x reference)
; __device__ __forceinline__ u32x4 pack8(f32x4 a, f32x4 b) { u32x4 w; w.x = cvt_pk_bf16(a[0], a[1]); w.y = cvt_pk_bf16(a[2], a[3]); w.z = cvt_pk_bf16(b[0], b[1]); w.w = cvt_pk_bf16(b[2], b[3]); return w; }
; template <bool P3> __device__ __forceinline__ void ssm_unit(CArgs* ap, const float* COEF, int l, const bf16_t* PROJ, float* SST, bf16_t* YS, LAS unsigned char* wlds, int unit, int lane) {
;     ...
;     for (int cb = 0; cb < 4; ++cb) {
;         const int gp = (l * 32 + g) * 64 + 16 * cb + fr;
;         const f32x4 cf = *(const f32x4*)(COEF + (size_t)(g * 64 + 16 * cb + fr) * 4);
;         const float abr = cf[0], abi = cf[1];
;         pr[cb][0] = abr; pi[cb][0] = abi;
; #pragma unroll
;         for (int i = 1; i < 4; ++i) { pr[cb][i] = pr[cb][i - 1] * abr - pi[cb][i - 1] * abi; pi[cb][i] = pr[cb][i - 1] * abi + pi[cb][i - 1] * abr; }
;         const float cr = cf[2], ci = cf[3];
;         u32x4 wre = {0u, 0u, 0u, 0u}, wim = {0u, 0u, 0u, 0u};
;         if (fq < 2) {
;             const float* br = ap->in[14] + (size_t)gp * 16 + 8 * fq; const float* bi = ap->in[15] + (size_t)gp * 16 + 8 * fq;
;             const f32x4 r0 = *(const f32x4*)br, r1 = *(const f32x4*)(br + 4), i0 = *(const f32x4*)bi, i1 = *(const f32x4*)(bi + 4);
;             wre = pg8::pack8(cr * r0 - ci * i0, cr * r1 - ci * i1); wim = pg8::pack8(cr * i0 + ci * r0, cr * i1 + ci * r1);
;         }
;         bfr[cb] = as_bf8(wre); bfr[cb + 4] = as_bf8(wim);
;     }
.LBB0_247:
	s_bfe_u32 s3, s2, 0x50006
	s_lshl_b32 s12, s3, 6
	v_or_b32_e32 v0, s12, v70
	v_readlane_b32 s10, v254, 18
	v_lshlrev_b32_e32 v0, 4, v0
	v_readlane_b32 s11, v254, 19
	s_waitcnt vmcnt(0)
	v_or_b32_e32 v52, s12, v73
	v_mov_b32_e32 v14, 0
	s_waitcnt vmcnt(4)
	v_lshlrev_b32_e32 v50, 2, v72
	v_mov_b32_e32 v10, 0
	v_mov_b32_e32 v11, 0
	global_load_dwordx4 v[2:5], v0, s[10:11]
	global_load_dwordx4 v[240:243], v0, s[10:11] offset:256
	global_load_dwordx4 v[244:247], v0, s[10:11] offset:512
	global_load_dwordx4 v[248:251], v0, s[10:11] offset:768
	v_mov_b32_e32 v12, 0
	v_mov_b32_e32 v13, 0
	v_mov_b32_e32 v6, 0
	v_mov_b32_e32 v7, 0
	v_mov_b32_e32 v8, 0
	v_mov_b32_e32 v9, 0
	s_and_saveexec_b64 s[10:11], s[0:1]
	s_cbranch_execz .LBB0_249
	s_load_dwordx4 s[16:19], s[82:83], 0x70
	v_ashrrev_i32_e32 v53, 31, v52
	v_lshlrev_b64 v[16:17], 6, v[52:53]
	v_mov_b32_e32 v51, v1
	s_waitcnt vmcnt(0)
	v_mov_b32_e32 v24, v5
	s_waitcnt lgkmcnt(0)
	v_lshl_add_u64 v[6:7], s[18:19], 0, v[16:17]
	v_lshl_add_u64 v[10:11], v[6:7], 0, v[50:51]
	v_lshl_add_u64 v[16:17], s[16:17], 0, v[16:17]
	global_load_dwordx4 v[6:9], v[10:11], off
	s_nop 0
	global_load_dwordx4 v[10:13], v[10:11], off offset:16
	v_lshl_add_u64 v[20:21], v[16:17], 0, v[50:51]
	global_load_dwordx4 v[16:19], v[20:21], off
	s_nop 0
	global_load_dwordx4 v[20:23], v[20:21], off offset:16
	s_waitcnt vmcnt(3)
	v_pk_mul_f32 v[26:27], v[24:25], v[8:9] op_sel_hi:[0,1]
	s_waitcnt vmcnt(2)
	v_pk_mul_f32 v[30:31], v[24:25], v[12:13] op_sel_hi:[0,1]
	v_pk_mul_f32 v[32:33], v[24:25], v[10:11] op_sel_hi:[0,1]
	v_pk_mul_f32 v[12:13], v[4:5], v[12:13] op_sel_hi:[0,1]
	v_pk_mul_f32 v[10:11], v[4:5], v[10:11] op_sel_hi:[0,1]
	v_pk_mul_f32 v[28:29], v[24:25], v[6:7] op_sel_hi:[0,1]
	v_pk_mul_f32 v[8:9], v[4:5], v[8:9] op_sel_hi:[0,1]
	v_pk_mul_f32 v[6:7], v[4:5], v[6:7] op_sel_hi:[0,1]
	s_waitcnt vmcnt(0)
	v_pk_fma_f32 v[30:31], v[4:5], v[22:23], v[30:31] op_sel_hi:[0,1,1] neg_lo:[0,0,1] neg_hi:[0,0,1]
	v_pk_fma_f32 v[22:23], v[24:25], v[22:23], v[12:13] op_sel_hi:[0,1,1]
	v_pk_fma_f32 v[12:13], v[24:25], v[20:21], v[10:11] op_sel_hi:[0,1,1]
	v_pk_fma_f32 v[26:27], v[4:5], v[18:19], v[26:27] op_sel_hi:[0,1,1] neg_lo:[0,0,1] neg_hi:[0,0,1]
	v_pk_fma_f32 v[28:29], v[4:5], v[16:17], v[28:29] op_sel_hi:[0,1,1] neg_lo:[0,0,1] neg_hi:[0,0,1]
	v_pk_fma_f32 v[4:5], v[4:5], v[20:21], v[32:33] op_sel_hi:[0,1,1] neg_lo:[0,0,1] neg_hi:[0,0,1]
	v_pk_fma_f32 v[18:19], v[24:25], v[18:19], v[8:9] op_sel_hi:[0,1,1]
	v_pk_fma_f32 v[16:17], v[24:25], v[16:17], v[6:7] op_sel_hi:[0,1,1]
	v_cvt_pk_bf16_f32 v6, v28, v29
	v_cvt_pk_bf16_f32 v7, v26, v27
	v_cvt_pk_bf16_f32 v8, v4, v5
	v_cvt_pk_bf16_f32 v9, v30, v31
	v_cvt_pk_bf16_f32 v10, v16, v17
	v_cvt_pk_bf16_f32 v11, v18, v19
	v_cvt_pk_bf16_f32 v12, v12, v13
	v_cvt_pk_bf16_f32 v13, v22, v23
.LBB0_249:
	s_or_b64 exec, exec, s[10:11]
	v_readlane_b32 s10, v254, 18
	v_readlane_b32 s11, v254, 19
	v_mov_b32_e32 v15, 0
	v_mov_b32_e32 v16, 0
	s_waitcnt vmcnt(0)
	v_lshl_add_u64 v[4:5], s[10:11], 0, v[0:1]
	v_mov_b32_e32 v18, v240
	v_mov_b32_e32 v19, v241
	v_mov_b32_e32 v20, v242
	v_mov_b32_e32 v21, v243
	v_mov_b32_e32 v17, 0
	v_mov_b32_e32 v22, 0
	v_mov_b32_e32 v23, 0
	v_mov_b32_e32 v24, 0
	v_mov_b32_e32 v25, 0
	s_and_saveexec_b64 s[10:11], s[0:1]
	s_cbranch_execz .LBB0_251
	s_load_dwordx4 s[16:19], s[82:83], 0x70
	v_or_b32_e32 v14, 16, v52
	v_ashrrev_i32_e32 v15, 31, v14
	v_lshlrev_b64 v[26:27], 6, v[14:15]
	v_mov_b32_e32 v51, v1
	s_waitcnt lgkmcnt(0)
	v_lshl_add_u64 v[14:15], s[18:19], 0, v[26:27]
	v_lshl_add_u64 v[22:23], v[14:15], 0, v[50:51]
	v_lshl_add_u64 v[26:27], s[16:17], 0, v[26:27]
	global_load_dwordx4 v[14:17], v[22:23], off
	s_nop 0
	global_load_dwordx4 v[22:25], v[22:23], off offset:16
	v_lshl_add_u64 v[30:31], v[26:27], 0, v[50:51]
	global_load_dwordx4 v[26:29], v[30:31], off
	s_nop 0
	global_load_dwordx4 v[30:33], v[30:31], off offset:16
	s_waitcnt vmcnt(4)
	v_mov_b32_e32 v0, v21
	s_waitcnt vmcnt(3)
	v_pk_mul_f32 v[34:35], v[0:1], v[16:17] op_sel_hi:[0,1]
	v_pk_mul_f32 v[36:37], v[0:1], v[14:15] op_sel_hi:[0,1]
	v_pk_mul_f32 v[16:17], v[20:21], v[16:17] op_sel_hi:[0,1]
	v_pk_mul_f32 v[14:15], v[20:21], v[14:15] op_sel_hi:[0,1]
	s_waitcnt vmcnt(2)
	v_pk_mul_f32 v[38:39], v[0:1], v[24:25] op_sel_hi:[0,1]
	v_pk_mul_f32 v[40:41], v[0:1], v[22:23] op_sel_hi:[0,1]
	v_pk_mul_f32 v[24:25], v[20:21], v[24:25] op_sel_hi:[0,1]
	v_pk_mul_f32 v[22:23], v[20:21], v[22:23] op_sel_hi:[0,1]
	s_waitcnt vmcnt(1)
	v_pk_fma_f32 v[16:17], v[0:1], v[28:29], v[16:17] op_sel_hi:[0,1,1]
	v_pk_fma_f32 v[14:15], v[0:1], v[26:27], v[14:15] op_sel_hi:[0,1,1]
	v_pk_fma_f32 v[34:35], v[20:21], v[28:29], v[34:35] op_sel_hi:[0,1,1] neg_lo:[0,0,1] neg_hi:[0,0,1]
	v_pk_fma_f32 v[36:37], v[20:21], v[26:27], v[36:37] op_sel_hi:[0,1,1] neg_lo:[0,0,1] neg_hi:[0,0,1]
	s_waitcnt vmcnt(0)
	v_pk_fma_f32 v[38:39], v[20:21], v[32:33], v[38:39] op_sel_hi:[0,1,1] neg_lo:[0,0,1] neg_hi:[0,0,1]
	v_pk_fma_f32 v[20:21], v[20:21], v[30:31], v[40:41] op_sel_hi:[0,1,1] neg_lo:[0,0,1] neg_hi:[0,0,1]
	v_pk_fma_f32 v[26:27], v[0:1], v[32:33], v[24:25] op_sel_hi:[0,1,1]
	v_pk_fma_f32 v[28:29], v[0:1], v[30:31], v[22:23] op_sel_hi:[0,1,1]
	v_cvt_pk_bf16_f32 v22, v36, v37
	v_cvt_pk_bf16_f32 v23, v34, v35
	v_cvt_pk_bf16_f32 v24, v20, v21
	v_cvt_pk_bf16_f32 v25, v38, v39
	v_cvt_pk_bf16_f32 v14, v14, v15
	v_cvt_pk_bf16_f32 v15, v16, v17
	v_cvt_pk_bf16_f32 v16, v28, v29
	v_cvt_pk_bf16_f32 v17, v26, v27
; __device__ __forceinline__ u32x4 pack8(f32x4 a, f32x4 b) { u32x4 w; w.x = cvt_pk_bf16(a[0], a[1]); w.y = cvt_pk_bf16(a[2], a[3]); w.z = cvt_pk_bf16(b[0], b[1]); w.w = cvt_pk_bf16(b[2], b[3]); return w; }
; template <bool P3> __device__ __forceinline__ void ssm_unit(CArgs* ap, const float* COEF, int l, const bf16_t* PROJ, float* SST, bf16_t* YS, LAS unsigned char* wlds, int unit, int lane) {
;     ...
;     for (int cb = 0; cb < 4; ++cb) {
;         const int gp = (l * 32 + g) * 64 + 16 * cb + fr;
;         const f32x4 cf = *(const f32x4*)(COEF + (size_t)(g * 64 + 16 * cb + fr) * 4);
;         const float abr = cf[0], abi = cf[1];
;         pr[cb][0] = abr; pi[cb][0] = abi;
; #pragma unroll
;         for (int i = 1; i < 4; ++i) { pr[cb][i] = pr[cb][i - 1] * abr - pi[cb][i - 1] * abi; pi[cb][i] = pr[cb][i - 1] * abi + pi[cb][i - 1] * abr; }
;         const float cr = cf[2], ci = cf[3];
;         u32x4 wre = {0u, 0u, 0u, 0u}, wim = {0u, 0u, 0u, 0u};
;         if (fq < 2) {
;             const float* br = ap->in[14] + (size_t)gp * 16 + 8 * fq; const float* bi = ap->in[15] + (size_t)gp * 16 + 8 * fq;
;             const f32x4 r0 = *(const f32x4*)br, r1 = *(const f32x4*)(br + 4), i0 = *(const f32x4*)bi, i1 = *(const f32x4*)(bi + 4);
;             wre = pg8::pack8(cr * r0 - ci * i0, cr * r1 - ci * i1); wim = pg8::pack8(cr * i0 + ci * r0, cr * i1 + ci * r1);
;         }
;         bfr[cb] = as_bf8(wre); bfr[cb + 4] = as_bf8(wim);
;     }
.LBB0_251:
	s_or_b64 exec, exec, s[10:11]
	v_mov_b32_e32 v26, v244
	v_mov_b32_e32 v27, v245
	v_mov_b32_e32 v28, v246
	v_mov_b32_e32 v29, v247
	v_mov_b32_e32 v34, 0
	v_mov_b32_e32 v38, 0
	v_mov_b32_e32 v39, 0
	v_mov_b32_e32 v40, 0
	v_mov_b32_e32 v41, 0
	v_mov_b32_e32 v30, 0
	v_mov_b32_e32 v31, 0
	v_mov_b32_e32 v32, 0
	v_mov_b32_e32 v33, 0
	s_and_saveexec_b64 s[10:11], s[0:1]
	s_cbranch_execz .LBB0_253
	s_load_dwordx4 s[16:19], s[82:83], 0x70
	v_or_b32_e32 v4, 32, v52
	v_ashrrev_i32_e32 v5, 31, v4
	v_lshlrev_b64 v[4:5], 6, v[4:5]
	v_mov_b32_e32 v51, v1
	s_waitcnt vmcnt(1) lgkmcnt(0)
	v_lshl_add_u64 v[20:21], s[18:19], 0, v[4:5]
	v_lshl_add_u64 v[20:21], v[20:21], 0, v[50:51]
	v_lshl_add_u64 v[4:5], s[16:17], 0, v[4:5]
	global_load_dwordx4 v[30:33], v[20:21], off
	global_load_dwordx4 v[36:39], v[20:21], off offset:16
	v_lshl_add_u64 v[4:5], v[4:5], 0, v[50:51]
	global_load_dwordx4 v[40:43], v[4:5], off
	global_load_dwordx4 v[44:47], v[4:5], off offset:16
	s_waitcnt vmcnt(4)
	v_mov_b32_e32 v0, v29
	s_waitcnt vmcnt(3)
	v_pk_mul_f32 v[20:21], v[0:1], v[30:31] op_sel_hi:[0,1]
	v_pk_mul_f32 v[30:31], v[28:29], v[30:31] op_sel_hi:[0,1]
	v_pk_mul_f32 v[4:5], v[0:1], v[32:33] op_sel_hi:[0,1]
	s_waitcnt vmcnt(2)
	v_pk_mul_f32 v[48:49], v[0:1], v[38:39] op_sel_hi:[0,1]
	v_pk_mul_f32 v[54:55], v[0:1], v[36:37] op_sel_hi:[0,1]
	v_pk_mul_f32 v[32:33], v[28:29], v[32:33] op_sel_hi:[0,1]
	v_pk_mul_f32 v[38:39], v[28:29], v[38:39] op_sel_hi:[0,1]
	v_pk_mul_f32 v[36:37], v[28:29], v[36:37] op_sel_hi:[0,1]
	s_waitcnt vmcnt(1)
	v_pk_fma_f32 v[20:21], v[28:29], v[40:41], v[20:21] op_sel_hi:[0,1,1] neg_lo:[0,0,1] neg_hi:[0,0,1]
	v_pk_fma_f32 v[40:41], v[0:1], v[40:41], v[30:31] op_sel_hi:[0,1,1]
	v_pk_fma_f32 v[4:5], v[28:29], v[42:43], v[4:5] op_sel_hi:[0,1,1] neg_lo:[0,0,1] neg_hi:[0,0,1]
	s_waitcnt vmcnt(0)
	v_pk_fma_f32 v[48:49], v[28:29], v[46:47], v[48:49] op_sel_hi:[0,1,1] neg_lo:[0,0,1] neg_hi:[0,0,1]
	v_pk_fma_f32 v[28:29], v[28:29], v[44:45], v[54:55] op_sel_hi:[0,1,1] neg_lo:[0,0,1] neg_hi:[0,0,1]
	v_pk_fma_f32 v[42:43], v[0:1], v[42:43], v[32:33] op_sel_hi:[0,1,1]
	v_pk_fma_f32 v[46:47], v[0:1], v[46:47], v[38:39] op_sel_hi:[0,1,1]
	v_pk_fma_f32 v[36:37], v[0:1], v[44:45], v[36:37] op_sel_hi:[0,1,1]
	v_cvt_pk_bf16_f32 v30, v20, v21
	v_cvt_pk_bf16_f32 v31, v4, v5
	v_cvt_pk_bf16_f32 v32, v28, v29
	v_cvt_pk_bf16_f32 v33, v48, v49
	v_cvt_pk_bf16_f32 v38, v40, v41
	v_cvt_pk_bf16_f32 v39, v42, v43
	v_cvt_pk_bf16_f32 v40, v36, v37
	v_cvt_pk_bf16_f32 v41, v46, v47
.LBB0_253:
	s_or_b64 exec, exec, s[10:11]
	v_or_b32_e32 v0, s12, v166
	v_mov_b32_e32 v4, 0x300
	v_readlane_b32 s10, v254, 18
	v_lshl_or_b32 v0, v0, 4, v4
	v_readlane_b32 s11, v254, 19
	v_mov_b32_e32 v35, 0
	v_mov_b32_e32 v36, 0
	v_mov_b32_e32 v37, 0
	v_mov_b32_e32 v46, 0
	v_mov_b32_e32 v47, 0
	v_mov_b32_e32 v42, v248
	v_mov_b32_e32 v43, v249
	v_mov_b32_e32 v44, v250
	v_mov_b32_e32 v45, v251
	v_mov_b32_e32 v48, 0
	v_mov_b32_e32 v49, 0
	s_and_saveexec_b64 s[10:11], s[0:1]
	s_cbranch_execz .LBB0_255
	s_load_dwordx4 s[12:15], s[82:83], 0x70
	v_or_b32_e32 v4, 48, v52
	v_ashrrev_i32_e32 v5, 31, v4
	v_lshlrev_b64 v[4:5], 6, v[4:5]
	v_mov_b32_e32 v51, v1
	s_waitcnt vmcnt(2) lgkmcnt(0)
	v_lshl_add_u64 v[20:21], s[14:15], 0, v[4:5]
	v_lshl_add_u64 v[20:21], v[20:21], 0, v[50:51]
	v_lshl_add_u64 v[4:5], s[12:13], 0, v[4:5]
	global_load_dwordx4 v[34:37], v[20:21], off
	global_load_dwordx4 v[46:49], v[20:21], off offset:16
	v_lshl_add_u64 v[4:5], v[4:5], 0, v[50:51]
	global_load_dwordx4 v[50:53], v[4:5], off
	global_load_dwordx4 v[54:57], v[4:5], off offset:16
	s_waitcnt vmcnt(4)
	v_mov_b32_e32 v0, v45
	s_waitcnt vmcnt(3)
	v_pk_mul_f32 v[4:5], v[0:1], v[36:37] op_sel_hi:[0,1]
	v_pk_mul_f32 v[20:21], v[0:1], v[34:35] op_sel_hi:[0,1]
	v_pk_mul_f32 v[36:37], v[44:45], v[36:37] op_sel_hi:[0,1]
	v_pk_mul_f32 v[34:35], v[44:45], v[34:35] op_sel_hi:[0,1]
	s_waitcnt vmcnt(2)
	v_pk_mul_f32 v[28:29], v[0:1], v[48:49] op_sel_hi:[0,1]
	v_pk_mul_f32 v[58:59], v[0:1], v[46:47] op_sel_hi:[0,1]
	v_pk_mul_f32 v[48:49], v[44:45], v[48:49] op_sel_hi:[0,1]
	v_pk_mul_f32 v[46:47], v[44:45], v[46:47] op_sel_hi:[0,1]
	s_waitcnt vmcnt(1)
	v_pk_fma_f32 v[36:37], v[0:1], v[52:53], v[36:37] op_sel_hi:[0,1,1]
	v_pk_fma_f32 v[34:35], v[0:1], v[50:51], v[34:35] op_sel_hi:[0,1,1]
	v_pk_fma_f32 v[4:5], v[44:45], v[52:53], v[4:5] op_sel_hi:[0,1,1] neg_lo:[0,0,1] neg_hi:[0,0,1]
	v_pk_fma_f32 v[20:21], v[44:45], v[50:51], v[20:21] op_sel_hi:[0,1,1] neg_lo:[0,0,1] neg_hi:[0,0,1]
	s_waitcnt vmcnt(0)
	v_pk_fma_f32 v[28:29], v[44:45], v[56:57], v[28:29] op_sel_hi:[0,1,1] neg_lo:[0,0,1] neg_hi:[0,0,1]
	v_pk_fma_f32 v[44:45], v[44:45], v[54:55], v[58:59] op_sel_hi:[0,1,1] neg_lo:[0,0,1] neg_hi:[0,0,1]
	v_pk_fma_f32 v[50:51], v[0:1], v[56:57], v[48:49] op_sel_hi:[0,1,1]
	v_pk_fma_f32 v[52:53], v[0:1], v[54:55], v[46:47] op_sel_hi:[0,1,1]
	v_cvt_pk_bf16_f32 v46, v20, v21
	v_cvt_pk_bf16_f32 v47, v4, v5
	v_cvt_pk_bf16_f32 v48, v44, v45
	v_cvt_pk_bf16_f32 v49, v28, v29
	v_cvt_pk_bf16_f32 v34, v34, v35
	v_cvt_pk_bf16_f32 v35, v36, v37
	v_cvt_pk_bf16_f32 v36, v52, v53
	v_cvt_pk_bf16_f32 v37, v50, v51

; template <class Epi, class Sched, bool ALIGN_EPI = false, bool SP2 = false>
; __device__ __forceinline__ void gemm_phase(PG8_LAS unsigned char* lds, const Gemm g, const Sched& S, const Epi& E, int wave_in) {
;     ...
;         const char* nA = has_next ? (const char*)g.A + (size_t)nxt.pm * tstepA : cA; const char* nB = has_next ? (const char*)g.Bt + (size_t)nxt.pn * tstep : cB;
;         for (int t = 0; t < nt; t += 2) {
;             const bool last = (t == nt - 2);
;             const char* a1 = cA + (size_t)(t + 1) * kstep;
;             const char* a2 = last ? nA : cA + (size_t)(t + 2) * kstep; const char* b2 = last ? nB : cB + (size_t)(t + 2) * kstep;
;             const char* a3 = a2 + kstep; const char* b3 = b2 + kstep;
;     ...
; #pragma unroll
;         for (int a = 0; a < 2; ++a)
; #pragma unroll
;             for (int b = 0; b < 2; ++b)
; #pragma unroll
;                 for (int m = 0; m < 4; ++m)
; #pragma unroll
;                     for (int n = 0; n < 2; ++n) acc[a][b][m][n] = (f32x4){0.f, 0.f, 0.f, 0.f};
;         cur = nxt; cA = nA; cB = nB; ++ui;
.LBB0_276:
	s_ashr_i32 s19, s18, 31
	s_lshl_b64 s[4:5], s[18:19], 20
	v_readlane_b32 s20, v253, 60
	v_readlane_b32 s21, v253, 61
	s_add_u32 s20, s20, s4
	s_load_dwordx2 s[22:23], s[82:83], 0xf8
	s_addc_u32 s21, s21, s5
	s_and_b64 s[4:5], s[6:7], exec
	s_cselect_b32 s19, s21, s1
	s_cselect_b32 s36, s20, s0
	s_ashr_i32 s17, s16, 31
	s_lshl_b64 s[4:5], s[16:17], 20
	s_waitcnt lgkmcnt(0)
	s_add_u32 s22, s22, s4
	s_addc_u32 s23, s23, s5
	s_and_b64 s[4:5], s[6:7], exec
	s_cselect_b32 s17, s23, s3
	s_cselect_b32 s37, s22, s2
	s_add_u32 s0, s0, 0x80080
	s_addc_u32 s1, s1, 0
	s_add_u32 s38, s2, 0x100
	v_mov_b32_e32 v2, 0
	s_addc_u32 s39, s3, 0
	s_mov_b32 s40, -2
	v_mov_b32_e32 v3, v2
	v_mov_b32_e32 v4, v2
	v_mov_b32_e32 v5, v2
	v_mov_b32_e32 v6, v2
	v_mov_b32_e32 v7, v2
	v_mov_b32_e32 v8, v2
	v_mov_b32_e32 v9, v2
	v_mov_b32_e32 v18, v2
	v_mov_b32_e32 v19, v2
	s_waitcnt vmcnt(0)
	v_mov_b32_e32 v20, v2
	v_mov_b32_e32 v21, v2
	v_mov_b32_e32 v22, v2
	v_mov_b32_e32 v23, v2
	v_mov_b32_e32 v24, v2
	v_mov_b32_e32 v25, v2
	v_mov_b32_e32 v50, v2
	v_mov_b32_e32 v51, v2
	v_mov_b32_e32 v52, v2
	v_mov_b32_e32 v53, v2
	v_mov_b32_e32 v54, v2
	v_mov_b32_e32 v55, v2
	v_mov_b32_e32 v56, v2
	v_mov_b32_e32 v57, v2
	v_mov_b32_e32 v66, v2
	v_mov_b32_e32 v67, v2
	v_mov_b32_e32 v68, v2
	v_mov_b32_e32 v69, v2
	v_mov_b32_e32 v70, v2
	v_mov_b32_e32 v71, v2
	v_mov_b32_e32 v72, v2
	v_mov_b32_e32 v73, v2
	v_mov_b32_e32 v10, v2
	v_mov_b32_e32 v11, v2
	v_mov_b32_e32 v12, v2
	v_mov_b32_e32 v13, v2
	v_mov_b32_e32 v14, v2
	v_mov_b32_e32 v15, v2
	v_mov_b32_e32 v16, v2
	v_mov_b32_e32 v17, v2
	v_mov_b32_e32 v34, v2
	v_mov_b32_e32 v35, v2
	v_mov_b32_e32 v36, v2
	v_mov_b32_e32 v37, v2
	v_mov_b32_e32 v38, v2
	v_mov_b32_e32 v39, v2
	v_mov_b32_e32 v40, v2
	v_mov_b32_e32 v41, v2
	v_mov_b32_e32 v58, v2
	v_mov_b32_e32 v59, v2
	v_mov_b32_e32 v60, v2
	v_mov_b32_e32 v61, v2
	v_mov_b32_e32 v62, v2
	v_mov_b32_e32 v63, v2
	v_mov_b32_e32 v64, v2
	v_mov_b32_e32 v65, v2
	v_mov_b32_e32 v74, v2
	v_mov_b32_e32 v75, v2
	v_mov_b32_e32 v76, v2
	v_mov_b32_e32 v77, v2
	v_mov_b32_e32 v78, v2
	v_mov_b32_e32 v79, v2
	v_mov_b32_e32 v80, v2
	v_mov_b32_e32 v81, v2
	v_mov_b32_e32 v82, v2
	v_mov_b32_e32 v83, v2
	v_mov_b32_e32 v84, v2
	v_mov_b32_e32 v85, v2
	v_mov_b32_e32 v86, v2
	v_mov_b32_e32 v87, v2
	v_mov_b32_e32 v88, v2
	v_mov_b32_e32 v89, v2
	v_mov_b32_e32 v98, v2
	v_mov_b32_e32 v99, v2
	v_mov_b32_e32 v100, v2
	v_mov_b32_e32 v101, v2
	v_mov_b32_e32 v102, v2
	v_mov_b32_e32 v103, v2
	v_mov_b32_e32 v104, v2
	v_mov_b32_e32 v105, v2
	v_mov_b32_e32 v114, v2
	v_mov_b32_e32 v115, v2
	v_mov_b32_e32 v116, v2
	v_mov_b32_e32 v117, v2
	v_mov_b32_e32 v118, v2
	v_mov_b32_e32 v119, v2
	v_mov_b32_e32 v120, v2
	v_mov_b32_e32 v121, v2
	v_mov_b32_e32 v130, v2
	v_mov_b32_e32 v131, v2
	v_mov_b32_e32 v132, v2
	v_mov_b32_e32 v133, v2
	v_mov_b32_e32 v134, v2
	v_mov_b32_e32 v135, v2
	v_mov_b32_e32 v136, v2
	v_mov_b32_e32 v137, v2
	v_mov_b32_e32 v90, v2
	v_mov_b32_e32 v91, v2
	v_mov_b32_e32 v92, v2
	v_mov_b32_e32 v93, v2
	v_mov_b32_e32 v94, v2
	v_mov_b32_e32 v95, v2
	v_mov_b32_e32 v96, v2
	v_mov_b32_e32 v97, v2
	v_mov_b32_e32 v106, v2
	v_mov_b32_e32 v107, v2
	v_mov_b32_e32 v108, v2
	v_mov_b32_e32 v109, v2
	v_mov_b32_e32 v110, v2
	v_mov_b32_e32 v111, v2
	v_mov_b32_e32 v112, v2
	v_mov_b32_e32 v113, v2
	v_mov_b32_e32 v122, v2
	v_mov_b32_e32 v123, v2
	v_mov_b32_e32 v124, v2
	v_mov_b32_e32 v125, v2
	v_mov_b32_e32 v126, v2
	v_mov_b32_e32 v127, v2
	v_mov_b32_e32 v128, v2
	v_mov_b32_e32 v129, v2
	v_mov_b32_e32 v138, v2
	v_mov_b32_e32 v139, v2
	v_mov_b32_e32 v140, v2
	v_mov_b32_e32 v141, v2
	v_mov_b32_e32 v142, v2
	v_mov_b32_e32 v143, v2
	v_mov_b32_e32 v144, v2
	v_mov_b32_e32 v145, v2
	s_nop 0
	s_nop 0
	s_nop 0
	s_nop 0
	s_nop 0
	s_nop 0
	s_nop 0
	s_nop 0
	s_nop 0
	s_nop 0
	s_nop 0
	s_nop 0
	s_nop 0
	s_nop 0
